# nt (streaming) output stores in in-proj (both copies) and ffn-up epilogues
# baseline (speedup 1.0000x reference)
.LBB0_61:
	v_mul_f32_e32 v147, 0xbfb8aa3b, v116
	v_exp_f32_e32 v147, v147
	v_mul_f32_e32 v146, 0xbfb8aa3b, v124
	v_exp_f32_e32 v146, v146
	s_ashr_i32 s55, s54, 31
	v_add_f32_e32 v147, 1.0, v147
	v_rcp_f32_e32 v148, v147
	v_mul_f32_e32 v147, 0xbfb8aa3b, v125
	v_exp_f32_e32 v147, v147
	v_add_f32_e32 v146, 1.0, v146
	v_rcp_f32_e32 v146, v146
	s_lshl_b64 s[0:1], s[54:55], 8
	v_add_f32_e32 v147, 1.0, v147
	v_rcp_f32_e32 v147, v147
	v_lshl_add_u64 v[144:145], v[136:137], 0, s[0:1]
	v_readlane_b32 s0, v253, 0
	v_readlane_b32 s1, v253, 1
	v_pk_mul_f32 v[124:125], v[124:125], v[146:147]
	s_load_dwordx16 s[4:19], s[0:1], 0xf0
	v_pk_mul_f32 v[120:121], v[124:125], v[120:121]
	v_mul_f32_e32 v124, 0xbfb8aa3b, v117
	v_exp_f32_e32 v124, v124
	s_lshl_b32 s54, s30, 7
	s_ashr_i32 s55, s54, 31
	s_mov_b64 s[20:21], -1
	v_add_f32_e32 v124, 1.0, v124
	v_rcp_f32_e32 v149, v124
	s_nop 0
	v_pk_mul_f32 v[116:117], v[116:117], v[148:149]
	s_nop 0
	v_pk_mul_f32 v[112:113], v[116:117], v[112:113]
	v_mul_f32_e32 v117, 0xbfb8aa3b, v118
	v_exp_f32_e32 v117, v117
	v_mul_f32_e32 v116, 0xbfb8aa3b, v126
	v_exp_f32_e32 v116, v116
	v_add_f32_e32 v117, 1.0, v117
	v_rcp_f32_e32 v124, v117
	v_mul_f32_e32 v117, 0xbfb8aa3b, v127
	v_exp_f32_e32 v117, v117
	v_add_f32_e32 v116, 1.0, v116
	v_rcp_f32_e32 v116, v116
	v_add_f32_e32 v117, 1.0, v117
	v_rcp_f32_e32 v117, v117
	s_nop 0
	v_pk_mul_f32 v[116:117], v[126:127], v[116:117]
	s_nop 0
	v_pk_mul_f32 v[116:117], v[116:117], v[122:123]
	v_mul_f32_e32 v122, 0xbfb8aa3b, v119
	v_exp_f32_e32 v122, v122
	s_nop 0
	v_add_f32_e32 v122, 1.0, v122
	v_rcp_f32_e32 v125, v122
	s_nop 0
	v_pk_mul_f32 v[118:119], v[118:119], v[124:125]
	s_nop 0
	v_pk_mul_f32 v[118:119], v[118:119], v[114:115]
	v_cvt_pk_bf16_f32 v115, v116, v117
	v_cvt_pk_bf16_f32 v116, v112, v113
	s_waitcnt lgkmcnt(0)
	v_mov_b64_e32 v[112:113], s[12:13]
	v_mad_u64_u32 v[112:113], s[0:1], v144, s96, v[112:113]
	v_cvt_pk_bf16_f32 v117, v118, v119
	v_mov_b32_e32 v118, v113
	v_mad_u64_u32 v[118:119], s[0:1], v145, s96, v[118:119]
	v_mov_b32_e32 v113, v118
	v_lshl_add_u64 v[112:113], s[54:55], 1, v[112:113]
	v_lshl_add_u64 v[112:113], v[112:113], 0, s[70:71]
	v_cvt_pk_bf16_f32 v114, v120, v121
	v_lshl_add_u64 v[112:113], v[112:113], 0, v[176:177]
	global_store_dwordx4 v[112:113], v[114:117], off nt
	s_mov_b32 s0, 0x16000
	s_nop 0
	v_mul_f32_e32 v115, 0xbfb8aa3b, v100
	v_exp_f32_e32 v115, v115
	v_mul_f32_e32 v114, 0xbfb8aa3b, v108
	v_exp_f32_e32 v114, v114
	v_add_f32_e32 v115, 1.0, v115
	v_rcp_f32_e32 v116, v115
	v_mul_f32_e32 v115, 0xbfb8aa3b, v109
	v_exp_f32_e32 v115, v115
	v_add_f32_e32 v114, 1.0, v114
	v_rcp_f32_e32 v114, v114
	v_add_f32_e32 v115, 1.0, v115
	v_rcp_f32_e32 v115, v115
	s_nop 0
	v_pk_mul_f32 v[108:109], v[108:109], v[114:115]
	s_nop 0
	v_pk_mul_f32 v[104:105], v[108:109], v[104:105]
	v_mul_f32_e32 v108, 0xbfb8aa3b, v101
	v_exp_f32_e32 v108, v108
	s_nop 0
	v_add_f32_e32 v108, 1.0, v108
	v_rcp_f32_e32 v117, v108
	s_nop 0
	v_pk_mul_f32 v[100:101], v[100:101], v[116:117]
	s_nop 0
	v_pk_mul_f32 v[100:101], v[100:101], v[96:97]
	v_mul_f32_e32 v97, 0xbfb8aa3b, v102
	v_exp_f32_e32 v97, v97
	v_mul_f32_e32 v96, 0xbfb8aa3b, v110
	v_exp_f32_e32 v96, v96
	v_add_f32_e32 v97, 1.0, v97
	v_rcp_f32_e32 v108, v97
	v_mul_f32_e32 v97, 0xbfb8aa3b, v111
	v_exp_f32_e32 v97, v97
	v_add_f32_e32 v96, 1.0, v96
	v_rcp_f32_e32 v96, v96
	v_add_f32_e32 v97, 1.0, v97
	v_rcp_f32_e32 v97, v97
	s_nop 0
	v_pk_mul_f32 v[96:97], v[110:111], v[96:97]
	s_nop 0
	v_pk_mul_f32 v[106:107], v[96:97], v[106:107]
	v_mul_f32_e32 v96, 0xbfb8aa3b, v103
	v_exp_f32_e32 v96, v96
	s_nop 0
	v_add_f32_e32 v96, 1.0, v96
	v_rcp_f32_e32 v109, v96
	s_nop 0
	v_pk_mul_f32 v[96:97], v[102:103], v[108:109]
	s_nop 0
	v_pk_mul_f32 v[102:103], v[96:97], v[98:99]
	v_cvt_pk_bf16_f32 v98, v100, v101
	v_add_co_u32_e32 v100, vcc, s0, v112
	v_cvt_pk_bf16_f32 v96, v104, v105
	v_cvt_pk_bf16_f32 v97, v106, v107
	v_cvt_pk_bf16_f32 v99, v102, v103
	v_addc_co_u32_e32 v101, vcc, 0, v113, vcc
	global_store_dwordx4 v[100:101], v[96:99], off nt
	s_mov_b32 s0, 0x2c000
	s_nop 0
	v_mul_f32_e32 v97, 0xbfb8aa3b, v84
	v_exp_f32_e32 v97, v97
	v_mul_f32_e32 v96, 0xbfb8aa3b, v92
	v_exp_f32_e32 v96, v96
	v_add_f32_e32 v97, 1.0, v97
	v_rcp_f32_e32 v98, v97
	v_mul_f32_e32 v97, 0xbfb8aa3b, v93
	v_exp_f32_e32 v97, v97
	v_add_f32_e32 v96, 1.0, v96
	v_rcp_f32_e32 v96, v96
	v_add_f32_e32 v97, 1.0, v97
	v_rcp_f32_e32 v97, v97
	s_nop 0
	v_pk_mul_f32 v[92:93], v[92:93], v[96:97]
	s_nop 0
	v_pk_mul_f32 v[88:89], v[92:93], v[88:89]
	v_mul_f32_e32 v92, 0xbfb8aa3b, v85
	v_exp_f32_e32 v92, v92
	s_nop 0
	v_add_f32_e32 v92, 1.0, v92
	v_rcp_f32_e32 v99, v92
	s_nop 0
	v_pk_mul_f32 v[84:85], v[84:85], v[98:99]
	s_nop 0
	v_pk_mul_f32 v[84:85], v[84:85], v[80:81]
	v_mul_f32_e32 v81, 0xbfb8aa3b, v86
	v_exp_f32_e32 v81, v81
	v_mul_f32_e32 v80, 0xbfb8aa3b, v94
	v_exp_f32_e32 v80, v80
	v_add_f32_e32 v81, 1.0, v81
	v_rcp_f32_e32 v92, v81
	v_mul_f32_e32 v81, 0xbfb8aa3b, v95
	v_exp_f32_e32 v81, v81
	v_add_f32_e32 v80, 1.0, v80
	v_rcp_f32_e32 v80, v80
	v_add_f32_e32 v81, 1.0, v81
	v_rcp_f32_e32 v81, v81
	s_nop 0
	v_pk_mul_f32 v[80:81], v[94:95], v[80:81]
	s_nop 0
	v_pk_mul_f32 v[90:91], v[80:81], v[90:91]
	v_mul_f32_e32 v80, 0xbfb8aa3b, v87
	v_exp_f32_e32 v80, v80
	s_nop 0
	v_add_f32_e32 v80, 1.0, v80
	v_rcp_f32_e32 v93, v80
	s_nop 0
	v_pk_mul_f32 v[80:81], v[86:87], v[92:93]
	s_nop 0
	v_pk_mul_f32 v[86:87], v[80:81], v[82:83]
	v_cvt_pk_bf16_f32 v82, v84, v85
	v_add_co_u32_e32 v84, vcc, s0, v112
	v_cvt_pk_bf16_f32 v80, v88, v89
	v_cvt_pk_bf16_f32 v81, v90, v91
	v_cvt_pk_bf16_f32 v83, v86, v87
	v_addc_co_u32_e32 v85, vcc, 0, v113, vcc
	global_store_dwordx4 v[84:85], v[80:83], off nt
	s_mov_b32 s0, 0x42000
	s_nop 0
	v_mul_f32_e32 v81, 0xbfb8aa3b, v68
	v_exp_f32_e32 v81, v81
	v_mul_f32_e32 v80, 0xbfb8aa3b, v76
	v_exp_f32_e32 v80, v80
	v_add_f32_e32 v81, 1.0, v81
	v_rcp_f32_e32 v82, v81
	v_mul_f32_e32 v81, 0xbfb8aa3b, v77
	v_exp_f32_e32 v81, v81
	v_add_f32_e32 v80, 1.0, v80
	v_rcp_f32_e32 v80, v80
	v_add_f32_e32 v81, 1.0, v81
	v_rcp_f32_e32 v81, v81
	s_nop 0
	v_pk_mul_f32 v[76:77], v[76:77], v[80:81]
	s_nop 0
	v_pk_mul_f32 v[72:73], v[76:77], v[72:73]
	v_mul_f32_e32 v76, 0xbfb8aa3b, v69
	v_exp_f32_e32 v76, v76
	s_nop 0
	v_add_f32_e32 v76, 1.0, v76
	v_rcp_f32_e32 v83, v76
	s_nop 0
	v_pk_mul_f32 v[68:69], v[68:69], v[82:83]
	s_nop 0
	v_pk_mul_f32 v[68:69], v[68:69], v[64:65]
	v_mul_f32_e32 v65, 0xbfb8aa3b, v70
	v_exp_f32_e32 v65, v65
	v_mul_f32_e32 v64, 0xbfb8aa3b, v78
	v_exp_f32_e32 v64, v64
	v_add_f32_e32 v65, 1.0, v65
	v_rcp_f32_e32 v76, v65
	v_mul_f32_e32 v65, 0xbfb8aa3b, v79
	v_exp_f32_e32 v65, v65
	v_add_f32_e32 v64, 1.0, v64
	v_rcp_f32_e32 v64, v64
	v_add_f32_e32 v65, 1.0, v65
	v_rcp_f32_e32 v65, v65
	s_nop 0
	v_pk_mul_f32 v[64:65], v[78:79], v[64:65]
	s_nop 0
	v_pk_mul_f32 v[74:75], v[64:65], v[74:75]
	v_mul_f32_e32 v64, 0xbfb8aa3b, v71
	v_exp_f32_e32 v64, v64
	s_nop 0
	v_add_f32_e32 v64, 1.0, v64
	v_rcp_f32_e32 v77, v64
	s_nop 0
	v_pk_mul_f32 v[64:65], v[70:71], v[76:77]
	s_nop 0
	v_pk_mul_f32 v[70:71], v[64:65], v[66:67]
	v_cvt_pk_bf16_f32 v66, v68, v69
	v_add_co_u32_e32 v68, vcc, s0, v112
	v_cvt_pk_bf16_f32 v64, v72, v73
	v_cvt_pk_bf16_f32 v65, v74, v75
	v_cvt_pk_bf16_f32 v67, v70, v71
	v_addc_co_u32_e32 v69, vcc, 0, v113, vcc
	global_store_dwordx4 v[68:69], v[64:67], off nt
	s_mov_b32 s0, 0xb0000
	s_nop 0
	v_mul_f32_e32 v65, 0xbfb8aa3b, v52
	v_exp_f32_e32 v65, v65
	v_mul_f32_e32 v64, 0xbfb8aa3b, v60
	v_exp_f32_e32 v64, v64
	v_add_f32_e32 v65, 1.0, v65
	v_rcp_f32_e32 v66, v65
	v_mul_f32_e32 v65, 0xbfb8aa3b, v61
	v_exp_f32_e32 v65, v65
	v_add_f32_e32 v64, 1.0, v64
	v_rcp_f32_e32 v64, v64
	v_add_f32_e32 v65, 1.0, v65
	v_rcp_f32_e32 v65, v65
	s_nop 0
	v_pk_mul_f32 v[60:61], v[60:61], v[64:65]
	s_nop 0
	v_pk_mul_f32 v[56:57], v[60:61], v[56:57]
	v_mul_f32_e32 v60, 0xbfb8aa3b, v53
	v_exp_f32_e32 v60, v60
	s_nop 0
	v_add_f32_e32 v60, 1.0, v60
	v_rcp_f32_e32 v67, v60
	s_nop 0
	v_pk_mul_f32 v[52:53], v[52:53], v[66:67]
	s_nop 0
	v_pk_mul_f32 v[52:53], v[52:53], v[48:49]
	v_mul_f32_e32 v49, 0xbfb8aa3b, v54
	v_exp_f32_e32 v49, v49
	v_mul_f32_e32 v48, 0xbfb8aa3b, v62
	v_exp_f32_e32 v48, v48
	v_add_f32_e32 v49, 1.0, v49
	v_rcp_f32_e32 v60, v49
	v_mul_f32_e32 v49, 0xbfb8aa3b, v63
	v_exp_f32_e32 v49, v49
	v_add_f32_e32 v48, 1.0, v48
	v_rcp_f32_e32 v48, v48
	v_add_f32_e32 v49, 1.0, v49
	v_rcp_f32_e32 v49, v49
	s_nop 0
	v_pk_mul_f32 v[48:49], v[62:63], v[48:49]
	s_nop 0
	v_pk_mul_f32 v[58:59], v[48:49], v[58:59]
	v_mul_f32_e32 v48, 0xbfb8aa3b, v55
	v_exp_f32_e32 v48, v48
	s_nop 0
	v_add_f32_e32 v48, 1.0, v48
	v_rcp_f32_e32 v61, v48
	s_nop 0
	v_pk_mul_f32 v[48:49], v[54:55], v[60:61]
	s_nop 0
	v_pk_mul_f32 v[54:55], v[48:49], v[50:51]
	v_cvt_pk_bf16_f32 v50, v52, v53
	v_add_co_u32_e32 v52, vcc, s0, v112
	v_cvt_pk_bf16_f32 v48, v56, v57
	v_cvt_pk_bf16_f32 v49, v58, v59
	v_cvt_pk_bf16_f32 v51, v54, v55
	v_addc_co_u32_e32 v53, vcc, 0, v113, vcc
	global_store_dwordx4 v[52:53], v[48:51], off nt
	s_mov_b32 s0, 0xc6000
	s_nop 0
	v_mul_f32_e32 v49, 0xbfb8aa3b, v36
	v_exp_f32_e32 v49, v49
	v_mul_f32_e32 v48, 0xbfb8aa3b, v44
	v_exp_f32_e32 v48, v48
	v_add_f32_e32 v49, 1.0, v49
	v_rcp_f32_e32 v50, v49
	v_mul_f32_e32 v49, 0xbfb8aa3b, v45
	v_exp_f32_e32 v49, v49
	v_add_f32_e32 v48, 1.0, v48
	v_rcp_f32_e32 v48, v48
	v_add_f32_e32 v49, 1.0, v49
	v_rcp_f32_e32 v49, v49
	s_nop 0
	v_pk_mul_f32 v[44:45], v[44:45], v[48:49]
	s_nop 0
	v_pk_mul_f32 v[40:41], v[44:45], v[40:41]
	v_mul_f32_e32 v44, 0xbfb8aa3b, v37
	v_exp_f32_e32 v44, v44
	s_nop 0
	v_add_f32_e32 v44, 1.0, v44
	v_rcp_f32_e32 v51, v44
	s_nop 0
	v_pk_mul_f32 v[36:37], v[36:37], v[50:51]
	s_nop 0
	v_pk_mul_f32 v[36:37], v[36:37], v[32:33]
	v_mul_f32_e32 v33, 0xbfb8aa3b, v38
	v_exp_f32_e32 v33, v33
	v_mul_f32_e32 v32, 0xbfb8aa3b, v46
	v_exp_f32_e32 v32, v32
	v_add_f32_e32 v33, 1.0, v33
	v_rcp_f32_e32 v44, v33
	v_mul_f32_e32 v33, 0xbfb8aa3b, v47
	v_exp_f32_e32 v33, v33
	v_add_f32_e32 v32, 1.0, v32
	v_rcp_f32_e32 v32, v32
	v_add_f32_e32 v33, 1.0, v33
	v_rcp_f32_e32 v33, v33
	s_nop 0
	v_pk_mul_f32 v[32:33], v[46:47], v[32:33]
	s_nop 0
	v_pk_mul_f32 v[42:43], v[32:33], v[42:43]
	v_mul_f32_e32 v32, 0xbfb8aa3b, v39
	v_exp_f32_e32 v32, v32
	s_nop 0
	v_add_f32_e32 v32, 1.0, v32
	v_rcp_f32_e32 v45, v32
	s_nop 0
	v_pk_mul_f32 v[32:33], v[38:39], v[44:45]
	s_nop 0
	v_pk_mul_f32 v[38:39], v[32:33], v[34:35]
	v_cvt_pk_bf16_f32 v34, v36, v37
	v_add_co_u32_e32 v36, vcc, s0, v112
	v_cvt_pk_bf16_f32 v32, v40, v41
	v_cvt_pk_bf16_f32 v33, v42, v43
	v_cvt_pk_bf16_f32 v35, v38, v39
	v_addc_co_u32_e32 v37, vcc, 0, v113, vcc
	global_store_dwordx4 v[36:37], v[32:35], off nt
	s_mov_b32 s0, 0xdc000
	s_nop 0
	v_mul_f32_e32 v33, 0xbfb8aa3b, v20
	v_exp_f32_e32 v33, v33
	v_mul_f32_e32 v32, 0xbfb8aa3b, v28
	v_exp_f32_e32 v32, v32
	v_add_f32_e32 v33, 1.0, v33
	v_rcp_f32_e32 v34, v33
	v_mul_f32_e32 v33, 0xbfb8aa3b, v29
	v_exp_f32_e32 v33, v33
	v_add_f32_e32 v32, 1.0, v32
	v_rcp_f32_e32 v32, v32
	v_add_f32_e32 v33, 1.0, v33
	v_rcp_f32_e32 v33, v33
	s_nop 0
	v_pk_mul_f32 v[28:29], v[28:29], v[32:33]
	s_nop 0
	v_pk_mul_f32 v[24:25], v[28:29], v[24:25]
	v_mul_f32_e32 v28, 0xbfb8aa3b, v21
	v_exp_f32_e32 v28, v28
	s_nop 0
	v_add_f32_e32 v28, 1.0, v28
	v_rcp_f32_e32 v35, v28
	s_nop 0
	v_pk_mul_f32 v[20:21], v[20:21], v[34:35]
	s_nop 0
	v_pk_mul_f32 v[20:21], v[20:21], v[16:17]
	v_mul_f32_e32 v17, 0xbfb8aa3b, v22
	v_exp_f32_e32 v17, v17
	v_mul_f32_e32 v16, 0xbfb8aa3b, v30
	v_exp_f32_e32 v16, v16
	v_add_f32_e32 v17, 1.0, v17
	v_rcp_f32_e32 v28, v17
	v_mul_f32_e32 v17, 0xbfb8aa3b, v31
	v_exp_f32_e32 v17, v17
	v_add_f32_e32 v16, 1.0, v16
	v_rcp_f32_e32 v16, v16
	v_add_f32_e32 v17, 1.0, v17
	v_rcp_f32_e32 v17, v17
	s_nop 0
	v_pk_mul_f32 v[16:17], v[30:31], v[16:17]
	s_nop 0
	v_pk_mul_f32 v[26:27], v[16:17], v[26:27]
	v_mul_f32_e32 v16, 0xbfb8aa3b, v23
	v_exp_f32_e32 v16, v16
	s_nop 0
	v_add_f32_e32 v16, 1.0, v16
	v_rcp_f32_e32 v29, v16
	s_nop 0
	v_pk_mul_f32 v[16:17], v[22:23], v[28:29]
	s_nop 0
	v_pk_mul_f32 v[22:23], v[16:17], v[18:19]
	v_cvt_pk_bf16_f32 v18, v20, v21
	v_add_co_u32_e32 v20, vcc, s0, v112
	v_cvt_pk_bf16_f32 v16, v24, v25
	v_cvt_pk_bf16_f32 v17, v26, v27
	v_cvt_pk_bf16_f32 v19, v22, v23
	v_addc_co_u32_e32 v21, vcc, 0, v113, vcc
	global_store_dwordx4 v[20:21], v[16:19], off nt
	s_nop 1
	v_mul_f32_e32 v17, 0xbfb8aa3b, v4
	v_exp_f32_e32 v17, v17
	v_mul_f32_e32 v16, 0xbfb8aa3b, v12
	v_exp_f32_e32 v16, v16
	v_add_f32_e32 v17, 1.0, v17
	v_rcp_f32_e32 v18, v17
	v_mul_f32_e32 v17, 0xbfb8aa3b, v13
	v_exp_f32_e32 v17, v17
	v_add_f32_e32 v16, 1.0, v16
	v_rcp_f32_e32 v16, v16
	v_add_f32_e32 v17, 1.0, v17
	v_rcp_f32_e32 v17, v17
	s_nop 0
	v_pk_mul_f32 v[12:13], v[12:13], v[16:17]
	s_nop 0
	v_pk_mul_f32 v[8:9], v[12:13], v[8:9]
	v_mul_f32_e32 v12, 0xbfb8aa3b, v5
	v_exp_f32_e32 v12, v12
	s_nop 0
	v_add_f32_e32 v12, 1.0, v12
	v_rcp_f32_e32 v19, v12
	s_nop 0
	v_pk_mul_f32 v[4:5], v[4:5], v[18:19]
	s_nop 0
	v_pk_mul_f32 v[4:5], v[4:5], v[0:1]
	v_mul_f32_e32 v1, 0xbfb8aa3b, v6
	v_exp_f32_e32 v1, v1
	v_mul_f32_e32 v0, 0xbfb8aa3b, v14
	v_exp_f32_e32 v0, v0
	v_add_f32_e32 v1, 1.0, v1
	v_rcp_f32_e32 v12, v1
	v_mul_f32_e32 v1, 0xbfb8aa3b, v15
	v_exp_f32_e32 v1, v1
	v_add_f32_e32 v0, 1.0, v0
	v_rcp_f32_e32 v0, v0
	v_add_f32_e32 v1, 1.0, v1
	v_rcp_f32_e32 v1, v1
	s_nop 0
	v_pk_mul_f32 v[0:1], v[14:15], v[0:1]
	s_nop 0
	v_pk_mul_f32 v[10:11], v[0:1], v[10:11]
	v_mul_f32_e32 v0, 0xbfb8aa3b, v7
	v_exp_f32_e32 v0, v0
	s_nop 0
	v_add_f32_e32 v0, 1.0, v0
	v_rcp_f32_e32 v13, v0
	s_nop 0
	v_pk_mul_f32 v[0:1], v[6:7], v[12:13]
	s_nop 0
	v_pk_mul_f32 v[6:7], v[0:1], v[2:3]
	v_cvt_pk_bf16_f32 v2, v4, v5
	v_add_co_u32_e32 v4, vcc, 0xf2000, v112
	v_cvt_pk_bf16_f32 v0, v8, v9
	s_nop 0
	v_addc_co_u32_e32 v5, vcc, 0, v113, vcc
	v_cvt_pk_bf16_f32 v1, v10, v11
	v_cvt_pk_bf16_f32 v3, v6, v7
	s_andn2_b64 vcc, exec, s[52:53]
	global_store_dwordx4 v[4:5], v[0:3], off nt
	s_cbranch_vccnz .LBB0_40
	v_readlane_b32 s0, v252, 26
	v_readlane_b32 s1, v252, 27
	s_andn2_b64 vcc, exec, s[0:1]
	s_cbranch_vccnz .LBB0_39
	s_barrier
	s_branch .LBB0_39
